# v33
# speedup vs baseline: 1.3639x; 1.0259x over previous
.LBB0_209:
	s_lshl_b32 s2, s15, 10
	s_xor_b64 s[8:9], s[10:11], -1
	s_add_i32 s10, s41, s2
	s_mov_b32 s11, 0
	v_mov_b32_e32 v18, v48
	v_mov_b32_e32 v236, v67
	v_mov_b32_e32 v237, v68
	v_mov_b32_e32 v238, v69
	v_mov_b32_e32 v239, v70
	v_and_b32_e32 v240, 3, v178
	v_lshlrev_b32_e32 v240, 5, v240
.LBB0_210:
	s_add_i32 s2, s10, s11
	v_add_u32_e32 v19, s2, v240
	ds_read_b128 v[34:37], v19
	ds_read_b128 v[38:41], v19 offset:16
	s_waitcnt lgkmcnt(1)
	v_mfma_f32_4x4x4_16b_bf16 v[228:231], v[34:35], v[54:55], 0
	v_mfma_f32_4x4x4_16b_bf16 v[232:235], v[34:35], v[56:57], 0
	s_nop 0
	v_mfma_f32_4x4x4_16b_bf16 v[228:231], v[36:37], v[58:59], v[228:231]
	v_mfma_f32_4x4x4_16b_bf16 v[232:235], v[36:37], v[60:61], v[232:235]
	s_waitcnt lgkmcnt(0)
	v_mfma_f32_4x4x4_16b_bf16 v[228:231], v[38:39], v[62:63], v[228:231]
	v_mfma_f32_4x4x4_16b_bf16 v[232:235], v[38:39], v[64:65], v[232:235]
	s_nop 0
	v_mfma_f32_4x4x4_16b_bf16 v[228:231], v[40:41], v[236:237], v[228:231]
	v_mfma_f32_4x4x4_16b_bf16 v[232:235], v[40:41], v[238:239], v[232:235]
	s_nop 7
	v_fma_f32 v33, -v53, v66, v228
	v_fma_f32 v74, v53, v71, v232
	v_fmac_f32_e32 v33, v52, v71
	v_fmac_f32_e32 v74, v52, v66
	v_cvt_pk_bf16_f32 v20, v33, v1
	v_cvt_pk_bf16_f32 v21, v74, v1
	ds_write_b16 v18, v20
	ds_write_b16 v18, v21 offset:128
	v_fma_f32 v71, -v53, v74, v229
	v_fma_f32 v66, v53, v33, v233
	v_fmac_f32_e32 v71, v52, v33
	v_fmac_f32_e32 v66, v52, v74
	v_cvt_pk_bf16_f32 v20, v71, v1
	v_cvt_pk_bf16_f32 v21, v66, v1
	ds_write_b16 v18, v20 offset:272
	ds_write_b16 v18, v21 offset:400
	v_fma_f32 v33, -v53, v66, v230
	v_fma_f32 v74, v53, v71, v234
	v_fmac_f32_e32 v33, v52, v71
	v_fmac_f32_e32 v74, v52, v66
	v_cvt_pk_bf16_f32 v20, v33, v1
	v_cvt_pk_bf16_f32 v21, v74, v1
	ds_write_b16 v18, v20 offset:544
	ds_write_b16 v18, v21 offset:672
	v_fma_f32 v71, -v53, v74, v231
	v_fma_f32 v66, v53, v33, v235
	v_fmac_f32_e32 v71, v52, v33
	v_fmac_f32_e32 v66, v52, v74
	v_cvt_pk_bf16_f32 v20, v71, v1
	v_cvt_pk_bf16_f32 v21, v66, v1
	ds_write_b16 v18, v20 offset:816
	ds_write_b16 v18, v21 offset:944
	s_addk_i32 s11, 0x80
	v_add_u32_e32 v18, 0x440, v18
	s_cmpk_eq_i32 s11, 0x400
	s_cbranch_scc0 .LBB0_210
	s_waitcnt lgkmcnt(0)
	ds_read_b128 v[18:21], v51 offset:4096
	ds_read_b128 v[34:37], v51 offset:4160
	v_lshl_or_b32 v33, s15, 5, v46
	s_mov_b32 s15, 1
	s_mov_b64 s[10:11], 0
	s_and_b64 vcc, exec, s[8:9]
	s_waitcnt lgkmcnt(1)
	v_mfma_f32_16x16x32_bf16 v[18:21], v[18:21], v[2:5], 0
	s_waitcnt lgkmcnt(0)
	v_mfma_f32_16x16x32_bf16 v[18:21], v[34:37], v[6:9], v[18:21]
	ds_read_b128 v[34:37], v51 offset:4224
	s_waitcnt lgkmcnt(0)
	v_mfma_f32_16x16x32_bf16 v[18:21], v[34:37], v[10:13], v[18:21]
	ds_read_b128 v[34:37], v51 offset:4288
	s_waitcnt lgkmcnt(0)
	v_mfma_f32_16x16x32_bf16 v[18:21], v[34:37], v[14:17], v[18:21]
	v_lshl_add_u32 v34, v33, 5, v47
	ds_read_u16 v34, v34
	s_waitcnt lgkmcnt(0)
	v_lshlrev_b32_e32 v34, 16, v34
	s_nop 3
	v_fma_f32 v18, v0, v34, v18
	v_mul_f32_e32 v34, 0x3d372713, v18
	v_mul_f32_e32 v34, v18, v34
	v_fma_f32 v34, v18, v34, v18
	v_mul_f32_e32 v34, 0xbfcc422a, v34
	v_mul_f32_e32 v34, 0x3fb8aa3b, v34
	v_exp_f32_e32 v34, v34
	s_nop 0
	v_add_f32_e32 v34, 1.0, v34
	v_rcp_f32_e32 v34, v34
	s_nop 0
	v_mul_f32_e32 v18, v18, v34
	v_or_b32_e32 v34, s14, v33
	v_ashrrev_i32_e32 v35, 31, v34
	v_lshlrev_b64 v[34:35], 10, v[34:35]
	v_cvt_pk_bf16_f32 v18, v18, v1
	v_lshl_add_u64 v[34:35], v[30:31], 0, v[34:35]
	global_store_short v[34:35], v18, off
	v_or_b32_e32 v18, 1, v33
	v_lshl_add_u32 v34, v18, 5, v47
	ds_read_u16 v34, v34
	v_or_b32_e32 v18, s14, v18
	s_waitcnt lgkmcnt(0)
	v_lshlrev_b32_e32 v34, 16, v34
	v_fma_f32 v19, v0, v34, v19
	v_mul_f32_e32 v34, 0x3d372713, v19
	v_mul_f32_e32 v34, v19, v34
	v_fma_f32 v34, v19, v34, v19
	v_mul_f32_e32 v34, 0xbfcc422a, v34
	v_mul_f32_e32 v34, 0x3fb8aa3b, v34
	v_exp_f32_e32 v34, v34
	s_nop 0
	v_add_f32_e32 v34, 1.0, v34
	v_rcp_f32_e32 v34, v34
	s_nop 0
	v_mul_f32_e32 v19, v19, v34
	v_cvt_pk_bf16_f32 v34, v19, v1
	v_ashrrev_i32_e32 v19, 31, v18
	v_lshlrev_b64 v[18:19], 10, v[18:19]
	v_lshl_add_u64 v[18:19], v[30:31], 0, v[18:19]
	global_store_short v[18:19], v34, off
	v_or_b32_e32 v18, 2, v33
	v_lshl_add_u32 v19, v18, 5, v47
	ds_read_u16 v19, v19
	ds_read_b128 v[34:37], v51 offset:8512
	v_or_b32_e32 v18, s14, v18
	s_waitcnt lgkmcnt(1)
	v_lshlrev_b32_e32 v19, 16, v19
	v_fma_f32 v19, v0, v19, v20
	v_mul_f32_e32 v20, 0x3d372713, v19
	v_mul_f32_e32 v20, v19, v20
	v_fma_f32 v20, v19, v20, v19
	v_mul_f32_e32 v20, 0xbfcc422a, v20
	v_mul_f32_e32 v20, 0x3fb8aa3b, v20
	v_exp_f32_e32 v20, v20
	s_nop 0
	v_add_f32_e32 v20, 1.0, v20
	v_rcp_f32_e32 v20, v20
	s_nop 0
	v_mul_f32_e32 v19, v19, v20
	v_cvt_pk_bf16_f32 v20, v19, v1
	v_ashrrev_i32_e32 v19, 31, v18
	v_lshlrev_b64 v[18:19], 10, v[18:19]
	v_lshl_add_u64 v[18:19], v[30:31], 0, v[18:19]
	global_store_short v[18:19], v20, off
	v_or_b32_e32 v18, 3, v33
	v_lshl_add_u32 v19, v18, 5, v47
	ds_read_u16 v19, v19
	v_or_b32_e32 v18, s14, v18
	s_waitcnt lgkmcnt(0)
	v_lshlrev_b32_e32 v19, 16, v19
	v_fmac_f32_e32 v21, v0, v19
	v_mul_f32_e32 v19, 0x3d372713, v21
	v_mul_f32_e32 v19, v21, v19
	v_fma_f32 v19, v21, v19, v21
	v_mul_f32_e32 v19, 0xbfcc422a, v19
	v_mul_f32_e32 v19, 0x3fb8aa3b, v19
	v_exp_f32_e32 v19, v19
	s_nop 0
	v_add_f32_e32 v19, 1.0, v19
	v_rcp_f32_e32 v19, v19
	s_nop 0
	v_mul_f32_e32 v19, v21, v19
	v_cvt_pk_bf16_f32 v20, v19, v1
	v_ashrrev_i32_e32 v19, 31, v18
	v_lshlrev_b64 v[18:19], 10, v[18:19]
	v_lshl_add_u64 v[18:19], v[30:31], 0, v[18:19]
	global_store_short v[18:19], v20, off
	ds_read_b128 v[18:21], v51 offset:8448
	s_waitcnt lgkmcnt(0)
	v_mfma_f32_16x16x32_bf16 v[18:21], v[18:21], v[2:5], 0
	v_mfma_f32_16x16x32_bf16 v[18:21], v[34:37], v[6:9], v[18:21]
	ds_read_b128 v[34:37], v51 offset:8576
	s_waitcnt lgkmcnt(0)
	v_mfma_f32_16x16x32_bf16 v[18:21], v[34:37], v[10:13], v[18:21]
	ds_read_b128 v[34:37], v51 offset:8640
	s_waitcnt lgkmcnt(0)
	v_mfma_f32_16x16x32_bf16 v[18:21], v[34:37], v[14:17], v[18:21]
	v_or_b32_e32 v34, 16, v33
	v_lshl_add_u32 v35, v34, 5, v47
	ds_read_u16 v35, v35
	v_or_b32_e32 v34, s14, v34
	s_waitcnt lgkmcnt(0)
	v_lshlrev_b32_e32 v35, 16, v35
	s_nop 1
	v_fma_f32 v18, v0, v35, v18
	v_mul_f32_e32 v35, 0x3d372713, v18
	v_mul_f32_e32 v35, v18, v35
	v_fma_f32 v35, v18, v35, v18
	v_mul_f32_e32 v35, 0xbfcc422a, v35
	v_mul_f32_e32 v35, 0x3fb8aa3b, v35
	v_exp_f32_e32 v35, v35
	s_nop 0
	v_add_f32_e32 v35, 1.0, v35
	v_rcp_f32_e32 v35, v35
	s_nop 0
	v_mul_f32_e32 v18, v18, v35
	v_ashrrev_i32_e32 v35, 31, v34
	v_lshlrev_b64 v[34:35], 10, v[34:35]
	v_cvt_pk_bf16_f32 v18, v18, v1
	v_lshl_add_u64 v[34:35], v[30:31], 0, v[34:35]
	global_store_short v[34:35], v18, off
	v_or_b32_e32 v18, 17, v33
	v_lshl_add_u32 v34, v18, 5, v47
	ds_read_u16 v34, v34
	v_or_b32_e32 v18, s14, v18
	s_waitcnt lgkmcnt(0)
	v_lshlrev_b32_e32 v34, 16, v34
	v_fma_f32 v19, v0, v34, v19
	v_mul_f32_e32 v34, 0x3d372713, v19
	v_mul_f32_e32 v34, v19, v34
	v_fma_f32 v34, v19, v34, v19
	v_mul_f32_e32 v34, 0xbfcc422a, v34
	v_mul_f32_e32 v34, 0x3fb8aa3b, v34
	v_exp_f32_e32 v34, v34
	s_nop 0
	v_add_f32_e32 v34, 1.0, v34
	v_rcp_f32_e32 v34, v34
	s_nop 0
	v_mul_f32_e32 v19, v19, v34
	v_cvt_pk_bf16_f32 v34, v19, v1
	v_ashrrev_i32_e32 v19, 31, v18
	v_lshlrev_b64 v[18:19], 10, v[18:19]
	v_lshl_add_u64 v[18:19], v[30:31], 0, v[18:19]
	global_store_short v[18:19], v34, off
	v_or_b32_e32 v18, 18, v33
	v_lshl_add_u32 v19, v18, 5, v47
	ds_read_u16 v19, v19
	v_or_b32_e32 v18, s14, v18
	s_waitcnt lgkmcnt(0)
	v_lshlrev_b32_e32 v19, 16, v19
	v_fma_f32 v19, v0, v19, v20
	v_mul_f32_e32 v20, 0x3d372713, v19
	v_mul_f32_e32 v20, v19, v20
	v_fma_f32 v20, v19, v20, v19
	v_mul_f32_e32 v20, 0xbfcc422a, v20
	v_mul_f32_e32 v20, 0x3fb8aa3b, v20
	v_exp_f32_e32 v20, v20
	s_nop 0
	v_add_f32_e32 v20, 1.0, v20
	v_rcp_f32_e32 v20, v20
	s_nop 0
	v_mul_f32_e32 v19, v19, v20
	v_cvt_pk_bf16_f32 v20, v19, v1
	v_ashrrev_i32_e32 v19, 31, v18
	v_lshlrev_b64 v[18:19], 10, v[18:19]
	v_lshl_add_u64 v[18:19], v[30:31], 0, v[18:19]
	global_store_short v[18:19], v20, off
	v_or_b32_e32 v18, 19, v33
	v_lshl_add_u32 v19, v18, 5, v47
	ds_read_u16 v19, v19
	v_or_b32_e32 v18, s14, v18
	s_waitcnt lgkmcnt(0)
	v_lshlrev_b32_e32 v19, 16, v19
	v_fmac_f32_e32 v21, v0, v19
	v_mul_f32_e32 v19, 0x3d372713, v21
	v_mul_f32_e32 v19, v21, v19
	v_fma_f32 v19, v21, v19, v21
	v_mul_f32_e32 v19, 0xbfcc422a, v19
	v_mul_f32_e32 v19, 0x3fb8aa3b, v19
	v_exp_f32_e32 v19, v19
	s_nop 0
	v_add_f32_e32 v19, 1.0, v19
	v_rcp_f32_e32 v19, v19
	s_nop 0
	v_mul_f32_e32 v19, v21, v19
	v_cvt_pk_bf16_f32 v20, v19, v1
	v_ashrrev_i32_e32 v19, 31, v18
	v_lshlrev_b64 v[18:19], 10, v[18:19]
	v_lshl_add_u64 v[18:19], v[30:31], 0, v[18:19]
	global_store_short v[18:19], v20, off
	s_waitcnt lgkmcnt(0)
	s_cbranch_vccz .LBB0_209
	s_add_i32 s13, s13, 1
	s_cmp_eq_u32 s13, 4
	s_cbranch_scc0 .LBB0_208
	s_load_dword s2, s[78:79], 0x0
	s_waitcnt lgkmcnt(0)
	s_lshl_b32 s2, s2, 3
	s_add_i32 s40, s2, s40
	s_cmpk_gt_i32 s40, 0x7ff
	s_cbranch_scc0 .LBB0_165

.LBB0_230:
	s_or_b32 s9, s8, s10
	v_lshl_add_u32 v28, s9, 6, v27
	v_mov_b64_e32 v[2:3], s[6:7]
	v_mad_i64_i32 v[2:3], s[22:23], v28, s86, v[2:3]
	global_load_dwordx4 v[28:31], v[2:3], off
	global_load_dwordx4 v[32:35], v[2:3], off offset:16
	v_mov_b32_e32 v2, 0
	s_mov_b32 s22, 0
	v_mov_b32_e32 v3, v2
	s_waitcnt vmcnt(1)
	ds_write_b128 v13, v[28:31]
	s_waitcnt vmcnt(0)
	ds_write_b128 v13, v[32:35] offset:16
	s_waitcnt lgkmcnt(0)
	v_mov_b32_e32 v228, v0
	v_mov_b32_e32 v229, v14
	v_mov_b32_e32 v230, v17
	v_mov_b32_e32 v231, v18
	v_mov_b32_e32 v232, v21
	v_mov_b32_e32 v233, v22
	v_mov_b32_e32 v234, v4
	v_mov_b32_e32 v235, v5
	v_mov_b32_e32 v236, v15
	v_mov_b32_e32 v237, v16
	v_mov_b32_e32 v238, v19
	v_mov_b32_e32 v239, v20
	v_mov_b32_e32 v240, v23
	v_mov_b32_e32 v241, v24
	v_mov_b32_e32 v242, v25
	v_mov_b32_e32 v243, v26
	v_and_b32_e32 v252, 3, v178
	v_lshlrev_b32_e32 v252, 5, v252
.LBB0_231:
	s_add_i32 s2, s27, s22
	v_add_u32_e32 v52, s2, v252
	ds_read_b128 v[28:31], v52
	ds_read_b128 v[32:35], v52 offset:16
	s_waitcnt lgkmcnt(1)
	v_mfma_f32_4x4x4_16b_bf16 v[244:247], v[28:29], v[228:229], 0
	v_mfma_f32_4x4x4_16b_bf16 v[248:251], v[28:29], v[236:237], 0
	s_nop 0
	v_mfma_f32_4x4x4_16b_bf16 v[244:247], v[30:31], v[230:231], v[244:247]
	v_mfma_f32_4x4x4_16b_bf16 v[248:251], v[30:31], v[238:239], v[248:251]
	s_waitcnt lgkmcnt(0)
	v_mfma_f32_4x4x4_16b_bf16 v[244:247], v[32:33], v[232:233], v[244:247]
	v_mfma_f32_4x4x4_16b_bf16 v[248:251], v[32:33], v[240:241], v[248:251]
	s_nop 0
	v_mfma_f32_4x4x4_16b_bf16 v[244:247], v[34:35], v[234:235], v[244:247]
	v_mfma_f32_4x4x4_16b_bf16 v[248:251], v[34:35], v[242:243], v[248:251]
	s_addk_i32 s22, 0x80
	s_nop 7
	v_fma_f32 v36, v10, v3, v244
	v_fma_f32 v37, v11, v2, v248
	v_fma_f32 v2, v8, v2, v36
	v_fma_f32 v3, v9, v3, v37
	v_fma_f32 v36, v10, v3, v245
	v_fma_f32 v37, v11, v2, v249
	v_fma_f32 v2, v8, v2, v36
	v_fma_f32 v3, v9, v3, v37
	v_fma_f32 v36, v10, v3, v246
	v_fma_f32 v37, v11, v2, v250
	v_fma_f32 v2, v8, v2, v36
	v_fma_f32 v3, v9, v3, v37
	v_fma_f32 v36, v10, v3, v247
	v_fma_f32 v37, v11, v2, v251
	v_fma_f32 v2, v8, v2, v36
	v_fma_f32 v3, v9, v3, v37
	s_cmpk_eq_i32 s22, 0x800
	s_cbranch_scc0 .LBB0_231
	s_add_i32 s22, s11, s9
	s_ashr_i32 s23, s22, 31
	s_lshl_b64 s[22:23], s[22:23], 9
	v_lshl_add_u64 v[28:29], v[6:7], 0, s[22:23]
	global_store_dwordx2 v[28:29], v[2:3], off
	s_waitcnt lgkmcnt(0)
	s_add_i32 s8, s8, 1
	s_cmp_eq_u32 s8, 4
	s_cbranch_scc0 .LBB0_230
	s_load_dword s2, s[78:79], 0x0
	s_waitcnt lgkmcnt(0)
	s_lshl_b32 s2, s2, 3
	s_add_i32 s26, s2, s26
	s_cmpk_gt_i32 s26, 0x7ff
	s_cbranch_scc0 .LBB0_221
